# w_ffn_up quantisation loop: all 16 loads of the 8 items issued before one wait (hipcc waited for every item's row-maximum right after its load), divisions after
# speedup vs baseline: 1.0048x; 1.0047x over previous
; __device__ __forceinline__ void quant_rows_i8(const bf16_t* src, unsigned char* dst, const unsigned* rmax, int R, int C, size_t gt, size_t NT) {
;     ...
;     for (size_t it0 = gt; it0 < tot; it0 += 8 * NT) { u32x4 w[8]; float inv[8];
; #pragma unroll
;         for (int k = 0; k < 8; ++k) { const size_t it = it0 + k * NT; if (it < tot) { w[k] = __builtin_nontemporal_load((const u32x4*)(src + it * 8));
;                 inv[k] = 127.0f / fmaxf(__uint_as_float(rmax[(int)(it / per)]) * 1.004f, 1e-30f); } }
.LBB0_2420:
	v_lshrrev_b64 v[32:33], 7, v[80:81]
	v_lshl_add_u64 v[30:31], s[86:87], 0, v[64:65]
	v_and_b32_e32 v32, -4, v32
	v_lshl_add_u64 v[82:83], s[24:25], 0, v[32:33]
	global_load_dwordx4 v[30:33], v[30:31], off nt
	s_nop 0
	global_load_dword v1, v[82:83], off
	v_lshl_add_u64 v[82:83], s[26:27], 0, v[80:81]
	v_cmp_gt_u64_e64 s[4:5], s[2:3], v[82:83]
	s_and_saveexec_b64 s[6:7], s[4:5]
	s_cbranch_execz .LBB0_2422
	v_lshrrev_b64 v[2:3], 7, v[82:83]
	v_and_b32_e32 v2, -4, v2
	v_lshl_add_u64 v[2:3], s[24:25], 0, v[2:3]
	global_load_dword v130, v[2:3], off
	v_lshl_add_u64 v[2:3], s[86:87], 0, v[62:63]
	global_load_dwordx4 v[2:5], v[2:3], off nt
.LBB0_2422:
	s_or_b64 exec, exec, s[6:7]
	v_lshl_add_u64 v[82:83], s[26:27], 0, v[82:83]
	v_cmp_gt_u64_e64 s[6:7], s[2:3], v[82:83]
	s_and_saveexec_b64 s[8:9], s[6:7]
	s_cbranch_execz .LBB0_2424
	v_lshl_add_u64 v[6:7], s[30:31], 0, v[80:81]
	v_lshrrev_b64 v[6:7], 7, v[6:7]
	v_and_b32_e32 v6, -4, v6
	v_lshl_add_u64 v[6:7], s[24:25], 0, v[6:7]
	global_load_dword v131, v[6:7], off
	v_lshl_add_u64 v[6:7], s[86:87], 0, v[36:37]
	global_load_dwordx4 v[6:9], v[6:7], off nt
.LBB0_2424:
	s_or_b64 exec, exec, s[8:9]
	v_lshl_add_u64 v[82:83], s[26:27], 0, v[82:83]
	v_cmp_gt_u64_e64 s[8:9], s[2:3], v[82:83]
	s_and_saveexec_b64 s[10:11], s[8:9]
	s_cbranch_execz .LBB0_2426
	v_lshl_add_u64 v[10:11], s[36:37], 0, v[80:81]
	v_lshrrev_b64 v[10:11], 7, v[10:11]
	v_and_b32_e32 v10, -4, v10
	v_lshl_add_u64 v[10:11], s[24:25], 0, v[10:11]
	global_load_dword v132, v[10:11], off
	v_lshl_add_u64 v[10:11], s[86:87], 0, v[40:41]
	global_load_dwordx4 v[10:13], v[10:11], off nt
.LBB0_2426:
	s_or_b64 exec, exec, s[10:11]
	v_lshl_add_u64 v[82:83], s[26:27], 0, v[82:83]
	v_cmp_gt_u64_e64 s[10:11], s[2:3], v[82:83]
	s_and_saveexec_b64 s[12:13], s[10:11]
	s_cbranch_execz .LBB0_2428
	v_lshl_add_u64 v[14:15], s[38:39], 0, v[80:81]
	v_lshrrev_b64 v[14:15], 7, v[14:15]
	v_and_b32_e32 v14, -4, v14
	v_lshl_add_u64 v[14:15], s[24:25], 0, v[14:15]
	global_load_dword v133, v[14:15], off
	v_lshl_add_u64 v[14:15], s[86:87], 0, v[44:45]
	global_load_dwordx4 v[14:17], v[14:15], off nt
.LBB0_2428:
	s_or_b64 exec, exec, s[12:13]
	v_lshl_add_u64 v[82:83], s[26:27], 0, v[82:83]
	v_cmp_gt_u64_e64 s[12:13], s[2:3], v[82:83]
	s_and_saveexec_b64 s[14:15], s[12:13]
	s_cbranch_execz .LBB0_2430
	v_lshl_add_u64 v[18:19], s[40:41], 0, v[80:81]
	v_lshrrev_b64 v[18:19], 7, v[18:19]
	v_and_b32_e32 v18, -4, v18
	v_lshl_add_u64 v[18:19], s[24:25], 0, v[18:19]
	global_load_dword v134, v[18:19], off
	v_lshl_add_u64 v[18:19], s[86:87], 0, v[48:49]
	global_load_dwordx4 v[18:21], v[18:19], off nt
.LBB0_2430:
	s_or_b64 exec, exec, s[14:15]
	v_lshl_add_u64 v[82:83], s[26:27], 0, v[82:83]
	v_cmp_gt_u64_e64 s[14:15], s[2:3], v[82:83]
	s_and_saveexec_b64 s[16:17], s[14:15]
	s_cbranch_execz .LBB0_2432
	v_lshl_add_u64 v[22:23], s[42:43], 0, v[80:81]
	v_lshrrev_b64 v[22:23], 7, v[22:23]
	v_and_b32_e32 v22, -4, v22
	v_lshl_add_u64 v[22:23], s[24:25], 0, v[22:23]
	global_load_dword v135, v[22:23], off
	v_lshl_add_u64 v[22:23], s[86:87], 0, v[52:53]
	global_load_dwordx4 v[22:25], v[22:23], off nt
.LBB0_2432:
	s_or_b64 exec, exec, s[16:17]
	v_lshl_add_u64 v[82:83], s[26:27], 0, v[82:83]
	v_cmp_gt_u64_e64 s[16:17], s[2:3], v[82:83]
	s_and_saveexec_b64 s[52:53], s[16:17]
	s_cbranch_execz .LBB0_2434
	v_lshl_add_u64 v[26:27], s[44:45], 0, v[80:81]
	v_lshrrev_b64 v[26:27], 7, v[26:27]
	v_and_b32_e32 v26, -4, v26
	v_lshl_add_u64 v[26:27], s[24:25], 0, v[26:27]
	global_load_dword v136, v[26:27], off
	v_lshl_add_u64 v[26:27], s[86:87], 0, v[56:57]
	global_load_dwordx4 v[26:29], v[26:27], off nt
; __device__ __forceinline__ float bf_lo(unsigned w) { return __uint_as_float(w << 16); }
; __device__ __forceinline__ float bf_hi(unsigned w) { return __uint_as_float(w & 0xffff0000u); }
; __device__ __forceinline__ void quant_rows_i8(const bf16_t* src, unsigned char* dst, const unsigned* rmax, int R, int C, size_t gt, size_t NT) {
;     ...
;                 inv[k] = 127.0f / fmaxf(__uint_as_float(rmax[(int)(it / per)]) * 1.004f, 1e-30f); } }
; #pragma unroll
;         for (int k = 0; k < 8; ++k) { const size_t it = it0 + k * NT; if (it < tot) { u32x2 o; o.x = q8_pack4(bf_lo(w[k].x), bf_hi(w[k].x), bf_lo(w[k].y), bf_hi(w[k].y), inv[k]); o.y = q8_pack4(bf_lo(w[k].z), bf_hi(w[k].z), bf_lo(w[k].w), bf_hi(w[k].w), inv[k]);
;                 *(u32x2*)(dst + it * 8) = o; } } }
.LBB0_2434:
	s_or_b64 exec, exec, s[52:53]
	s_waitcnt vmcnt(0)
	v_mul_f32_e32 v130, 0x3f808312, v130
	v_max_f32_e32 v130, 0xda24260, v130
	v_div_scale_f32 v69, vcc, v130, v130, s1
	v_rcp_f32_e32 v71, v69
	v_div_scale_f32 v73, vcc, s1, v130, s1
	v_fma_f32 v75, -v69, v71, 1.0
	v_fmac_f32_e32 v71, v75, v71
	v_mul_f32_e32 v75, v73, v71
	v_fma_f32 v76, -v69, v75, v73
	v_fmac_f32_e32 v75, v76, v71
	v_fma_f32 v69, -v69, v75, v73
	v_div_fmas_f32 v69, v69, v71, v75
	v_div_fixup_f32 v76, v69, v130, s1
	v_mul_f32_e32 v131, 0x3f808312, v131
	v_max_f32_e32 v131, 0xda24260, v131
	v_div_scale_f32 v69, vcc, v131, v131, s1
	v_rcp_f32_e32 v71, v69
	v_div_scale_f32 v73, vcc, s1, v131, s1
	v_fma_f32 v75, -v69, v71, 1.0
	v_fmac_f32_e32 v71, v75, v71
	v_mul_f32_e32 v75, v73, v71
	v_fma_f32 v77, -v69, v75, v73
	v_fmac_f32_e32 v75, v77, v71
	v_fma_f32 v69, -v69, v75, v73
	v_div_fmas_f32 v69, v69, v71, v75
	v_div_fixup_f32 v78, v69, v131, s1
	v_mul_f32_e32 v132, 0x3f808312, v132
	v_max_f32_e32 v132, 0xda24260, v132
	v_div_scale_f32 v69, vcc, v132, v132, s1
	v_rcp_f32_e32 v71, v69
	v_div_scale_f32 v73, vcc, s1, v132, s1
	v_fma_f32 v74, -v69, v71, 1.0
	v_fmac_f32_e32 v71, v74, v71
	v_mul_f32_e32 v74, v73, v71
	v_fma_f32 v75, -v69, v74, v73
	v_fmac_f32_e32 v74, v75, v71
	v_fma_f32 v69, -v69, v74, v73
	v_div_fmas_f32 v69, v69, v71, v74
	v_div_fixup_f32 v74, v69, v132, s1
	v_mul_f32_e32 v133, 0x3f808312, v133
	v_max_f32_e32 v133, 0xda24260, v133
	v_div_scale_f32 v69, vcc, v133, v133, s1
	v_rcp_f32_e32 v71, v69
	v_div_scale_f32 v72, vcc, s1, v133, s1
	v_fma_f32 v73, -v69, v71, 1.0
	v_fmac_f32_e32 v71, v73, v71
	v_mul_f32_e32 v73, v72, v71
	v_fma_f32 v75, -v69, v73, v72
	v_fmac_f32_e32 v73, v75, v71
	v_fma_f32 v69, -v69, v73, v72
	v_div_fmas_f32 v69, v69, v71, v73
	v_div_fixup_f32 v72, v69, v133, s1
	v_mul_f32_e32 v134, 0x3f808312, v134
	v_max_f32_e32 v134, 0xda24260, v134
	v_div_scale_f32 v69, vcc, v134, v134, s1
	v_rcp_f32_e32 v70, v69
	v_div_scale_f32 v71, vcc, s1, v134, s1
	v_fma_f32 v73, -v69, v70, 1.0
	v_fmac_f32_e32 v70, v73, v70
	v_mul_f32_e32 v73, v71, v70
	v_fma_f32 v75, -v69, v73, v71
	v_fmac_f32_e32 v73, v75, v70
	v_fma_f32 v69, -v69, v73, v71
	v_div_fmas_f32 v69, v69, v70, v73
	v_div_fixup_f32 v70, v69, v134, s1
	v_mul_f32_e32 v135, 0x3f808312, v135
	v_max_f32_e32 v135, 0xda24260, v135
	v_div_scale_f32 v68, vcc, v135, v135, s1
	v_rcp_f32_e32 v69, v68
	v_div_scale_f32 v71, vcc, s1, v135, s1
	v_fma_f32 v73, -v68, v69, 1.0
	v_fmac_f32_e32 v69, v73, v69
	v_mul_f32_e32 v73, v71, v69
	v_fma_f32 v75, -v68, v73, v71
	v_fmac_f32_e32 v73, v75, v69
	v_fma_f32 v68, -v68, v73, v71
	v_div_fmas_f32 v68, v68, v69, v73
	v_div_fixup_f32 v68, v68, v135, s1
	v_mul_f32_e32 v136, 0x3f808312, v136
	v_max_f32_e32 v136, 0xda24260, v136
	v_div_scale_f32 v67, vcc, v136, v136, s1
	v_rcp_f32_e32 v69, v67
	v_div_scale_f32 v71, vcc, s1, v136, s1
	v_fma_f32 v73, -v67, v69, 1.0
	v_fmac_f32_e32 v69, v73, v69
	v_mul_f32_e32 v73, v71, v69
	v_fma_f32 v75, -v67, v73, v71
	v_fmac_f32_e32 v73, v75, v69
	v_fma_f32 v67, -v67, v73, v71
	v_div_fmas_f32 v67, v67, v69, v73
	v_div_fixup_f32 v66, v67, v136, s1
	v_mul_f32_e32 v1, 0x3f808312, v1
	v_max_f32_e32 v1, 0xda24260, v1
	v_div_scale_f32 v67, s[52:53], v1, v1, s1
	v_rcp_f32_e32 v69, v67
	v_div_scale_f32 v71, vcc, s1, v1, s1
	v_lshlrev_b32_e32 v85, 16, v32
	v_fma_f32 v73, -v67, v69, 1.0
	v_fmac_f32_e32 v69, v73, v69
	v_mul_f32_e32 v73, v71, v69
	v_fma_f32 v75, -v67, v73, v71
	v_fmac_f32_e32 v73, v75, v69
	v_fma_f32 v67, -v67, v73, v71
	v_div_fmas_f32 v67, v67, v69, v73
	v_div_fixup_f32 v80, v67, v1, s1
	v_lshlrev_b32_e32 v84, 16, v30
	v_and_b32_e32 v87, 0xffff0000, v32
	v_and_b32_e32 v86, 0xffff0000, v30
	v_lshlrev_b32_e32 v89, 16, v33
	v_and_b32_e32 v33, 0xffff0000, v33
	v_and_b32_e32 v32, 0xffff0000, v31
	v_lshlrev_b32_e32 v88, 16, v31
	v_pk_fma_f32 v[30:31], v[84:85], v[80:81], s[48:49] op_sel_hi:[1,0,0]
	v_pk_fma_f32 v[84:85], v[86:87], v[80:81], s[48:49] op_sel_hi:[1,0,0]
	v_pk_fma_f32 v[32:33], v[32:33], v[80:81], s[48:49] op_sel_hi:[1,0,0]
	v_pk_fma_f32 v[86:87], v[88:89], v[80:81], s[48:49] op_sel_hi:[1,0,0]
	v_lshlrev_b32_e32 v1, 8, v85
	v_lshlrev_b32_e32 v67, 8, v84
	v_lshlrev_b32_e32 v33, 24, v33
	v_lshlrev_b32_e32 v32, 24, v32
	v_and_b32_e32 v1, 0xff00, v1
	v_and_b32_e32 v67, 0xff00, v67
	v_lshlrev_b32_e32 v69, 16, v87
	v_lshlrev_b32_e32 v71, 16, v86
	v_or_b32_sdwa v31, v33, v31 dst_sel:DWORD dst_unused:UNUSED_PAD src0_sel:DWORD src1_sel:BYTE_0
	v_or_b32_sdwa v30, v32, v30 dst_sel:DWORD dst_unused:UNUSED_PAD src0_sel:DWORD src1_sel:BYTE_0
	v_and_b32_e32 v69, 0xff0000, v69
	v_and_b32_e32 v71, 0xff0000, v71
	v_or_b32_e32 v1, v31, v1
	v_or_b32_e32 v30, v30, v67
	v_or_b32_e32 v31, v1, v69
	v_or_b32_e32 v30, v30, v71
	v_lshl_add_u64 v[32:33], s[86:87], 0, v[34:35]
	global_store_dwordx2 v[32:33], v[30:31], off
	s_and_saveexec_b64 s[52:53], s[4:5]
	s_cbranch_execnz .LBB0_2441
	s_or_b64 exec, exec, s[52:53]
	s_and_saveexec_b64 s[4:5], s[6:7]
	s_cbranch_execnz .LBB0_2442
